# on top of best: phase-0 x conversion loop with depth-2 prefetch (two row pairs in flight per wave)
# speedup vs baseline: 1.0029x; 1.0029x over previous
; #define IN(i) karg_in(A, i)
; __device__ __forceinline__ void p0_prologue(KArgs A, LAS unsigned char* lds, int G) {
;     ...
;     {
;         auto ldrows = [&](int m, f32x4 (&v)[8]) { const f32x4* xr = (const f32x4*)(IN(0) + (size_t)m * D) + 2 * lane;
; #pragma unroll
;             for (int h = 0; h < 4; ++h) { v[2 * h] = xr[128 * h]; v[2 * h + 1] = xr[128 * h + 1]; } };
;         int m = 2 * gw;
;         if (m < M) {
;             f32x4 v[8]; ldrows(m, v);
;             for (;;) {
;                 const int mn = m + 2 * NGW; const bool hn = mn < M; f32x4 w[8];
; #pragma unroll
;                 for (int i = 0; i < 8; ++i) w[i] = v[i];
;                 if (hn) ldrows(mn, w);
.LBB0_577:
	s_or_b64 exec, exec, s[10:11]
	s_cmpk_lt_i32 s4, 0x4000
	s_cbranch_scc0 .LBB0_586
	s_load_dwordx2 s[6:7], s[0:1], 0x0
	s_lshl_b32 s0, s4, 1
	s_ashr_i32 s1, s0, 31
	s_lshl_b64 s[4:5], s[0:1], 12
	v_lshlrev_b32_e32 v0, 5, v69
	s_waitcnt lgkmcnt(0)
	s_add_u32 s4, s6, s4
	s_addc_u32 s5, s7, s5
	v_lshl_add_u64 v[26:27], s[4:5], 0, v[0:1]
	global_load_dwordx4 v[2:5], v0, s[4:5] offset:16
	global_load_dwordx4 v[6:9], v0, s[4:5]
	global_load_dwordx4 v[10:13], v0, s[4:5] offset:2064
	global_load_dwordx4 v[14:17], v0, s[4:5] offset:2048
	s_mov_b64 s[4:5], 0x1000
	s_movk_i32 s1, 0x1000
	v_lshl_add_u64 v[18:19], v[26:27], 0, s[4:5]
	v_add_co_u32_e32 v28, vcc, s1, v26
	s_mov_b64 s[4:5], 0x1800
	s_nop 0
	v_addc_co_u32_e32 v29, vcc, 0, v27, vcc
	v_lshl_add_u64 v[26:27], v[26:27], 0, s[4:5]
	global_load_dwordx4 v[22:25], v[28:29], off
	s_nop 0
	global_load_dwordx4 v[18:21], v[18:19], off offset:16
	s_nop 0
	global_load_dwordx4 v[30:33], v[28:29], off offset:2048
	s_nop 0
	global_load_dwordx4 v[26:29], v[26:27], off offset:16
	v_lshl_add_u64 v[66:67], s[6:7], 0, v[0:1]
	v_add_u32_e32 v0, 64, v235
	s_waitcnt vmcnt(0)
	v_xor_b32_e32 v34, 1, v234
	v_cmp_lt_i32_e32 vcc, v34, v0
	s_lshl_b32 s4, s89, 4
	s_mov_b64 s[6:7], 0x4000000
	v_cndmask_b32_e32 v34, v234, v34, vcc
	v_lshlrev_b32_e32 v74, 2, v34
	v_xor_b32_e32 v34, 2, v234
	v_cmp_lt_i32_e32 vcc, v34, v0
	s_add_u32 s5, s14, 0x60000
	v_cmp_eq_u32_e64 s[42:43], 0, v69
	v_cndmask_b32_e32 v34, v234, v34, vcc
	v_lshlrev_b32_e32 v75, 2, v34
	v_xor_b32_e32 v34, 4, v234
	v_cmp_lt_i32_e32 vcc, v34, v0
	s_nop 1
	v_cndmask_b32_e32 v34, v234, v34, vcc
	v_lshlrev_b32_e32 v76, 2, v34
	v_xor_b32_e32 v34, 8, v234
	v_cmp_lt_i32_e32 vcc, v34, v0
	s_nop 1
	v_cndmask_b32_e32 v34, v234, v34, vcc
	v_lshlrev_b32_e32 v77, 2, v34
	v_xor_b32_e32 v34, 16, v234
	v_cmp_lt_i32_e32 vcc, v34, v0
	s_nop 1
	v_cndmask_b32_e32 v34, v234, v34, vcc
	v_lshlrev_b32_e32 v78, 2, v34
	v_xor_b32_e32 v34, 32, v234
	v_cmp_lt_i32_e32 vcc, v34, v0
	s_nop 1
	v_cndmask_b32_e32 v0, v234, v34, vcc
	v_lshlrev_b32_e32 v79, 2, v0
	v_lshlrev_b32_e32 v0, 4, v69
	v_lshl_add_u64 v[34:35], s[14:15], 0, v[0:1]
	v_lshl_add_u64 v[68:69], v[34:35], 0, s[6:7]
	s_movk_i32 s7, 0x1000
	s_addc_u32 s6, s15, 0
	s_add_i32 s10, s0, s4
	s_cmp_lt_i32 s10, 0x8000
	s_cbranch_scc0 .Lx_nopre
	s_mov_b32 s100, s10
	s_ashr_i32 s101, s100, 31
	s_lshl_b64 s[20:21], s[100:101], 12
	v_lshl_add_u64 v[92:93], v[66:67], 0, s[20:21]
	s_mov_b64 s[20:21], 0x1000
	v_lshl_add_u64 v[94:95], v[92:93], 0, s[20:21]
	global_load_dwordx4 v[34:37], v[92:93], off offset:16
	global_load_dwordx4 v[38:41], v[92:93], off
	global_load_dwordx4 v[42:45], v[92:93], off offset:2064
	global_load_dwordx4 v[46:49], v[92:93], off offset:2048
	global_load_dwordx4 v[50:53], v[94:95], off offset:16
	global_load_dwordx4 v[54:57], v[94:95], off
	global_load_dwordx4 v[58:61], v[94:95], off offset:2064
	global_load_dwordx4 v[62:65], v[94:95], off offset:2048

; __device__ __forceinline__ void p0_prologue(KArgs A, LAS unsigned char* lds, int G) {
;     ...
;             for (;;) {
;                 const int mn = m + 2 * NGW; const bool hn = mn < M; f32x4 w[8];
; #pragma unroll
;                 for (int i = 0; i < 8; ++i) w[i] = v[i];
;                 if (hn) ldrows(mn, w);
.LBB0_579:
.LBB0_580:
	s_add_i32 s10, s0, s4
	s_cmp_lt_i32 s10, 0x8000
	s_cselect_b64 s[14:15], -1, 0
	s_add_i32 s100, s10, s4
	s_cmp_lt_i32 s100, 0x8000
	s_cbranch_scc0 .Lx_a_noload
	s_ashr_i32 s101, s100, 31
	s_lshl_b64 s[20:21], s[100:101], 12
	v_lshl_add_u64 v[92:93], v[66:67], 0, s[20:21]
	s_mov_b64 s[20:21], 0x1000
	v_lshl_add_u64 v[94:95], v[92:93], 0, s[20:21]
	global_load_dwordx4 v[100:103], v[92:93], off offset:16
	global_load_dwordx4 v[104:107], v[92:93], off
	global_load_dwordx4 v[108:111], v[92:93], off offset:2064
	global_load_dwordx4 v[112:115], v[92:93], off offset:2048
	global_load_dwordx4 v[116:119], v[94:95], off offset:16
	global_load_dwordx4 v[120:123], v[94:95], off
	global_load_dwordx4 v[124:127], v[94:95], off offset:2064
	global_load_dwordx4 v[128:131], v[94:95], off offset:2048

; __device__ __forceinline__ unsigned pk2(float lo, float hi) { return pg8::cvt_pk_bf16(lo, hi); }
; __device__ __forceinline__ void p0_prologue(KArgs A, LAS unsigned char* lds, int G) {
;     ...
;                 if (lane == 0) { float* sx = (float*)(ws + WS_SSQ) + 3 * M; sx[m] = s0; sx[m + 1] = s1; }
;                 v4u* o16 = (v4u*)((bf16*)(ws + WS_XN) + (size_t)m * D) + lane;
; #pragma unroll
;                 for (int h = 0; h < 4; ++h) { v4u o; o.x = pk2(v[2 * h].x, v[2 * h].y); o.y = pk2(v[2 * h].z, v[2 * h].w); o.z = pk2(v[2 * h + 1].x, v[2 * h + 1].y); o.w = pk2(v[2 * h + 1].z, v[2 * h + 1].w); o16[64 * h] = o; }
;                 if (!hn) break;
;                 m = mn;
; #pragma unroll
;                 for (int i = 0; i < 8; ++i) v[i] = w[i];
.LBB0_584:
	s_or_b64 exec, exec, s[20:21]
	s_lshl_b64 s[20:21], s[0:1], 11
	v_lshl_add_u64 v[80:81], v[68:69], 0, s[20:21]
	v_cvt_pk_bf16_f32 v70, v6, v7
	v_cvt_pk_bf16_f32 v71, v8, v9
	s_waitcnt lgkmcnt(1)
	v_cvt_pk_bf16_f32 v72, v2, v3
	s_waitcnt lgkmcnt(0)
	v_cvt_pk_bf16_f32 v73, v4, v5
	global_store_dwordx4 v[80:81], v[70:73], off
	s_andn2_b64 vcc, exec, s[14:15]
	s_nop 0
	v_cvt_pk_bf16_f32 v70, v14, v15
	v_cvt_pk_bf16_f32 v71, v16, v17
	v_cvt_pk_bf16_f32 v72, v10, v11
	v_cvt_pk_bf16_f32 v73, v12, v13
	global_store_dwordx4 v[80:81], v[70:73], off offset:1024
	s_nop 1
	v_cvt_pk_bf16_f32 v70, v22, v23
	v_cvt_pk_bf16_f32 v71, v24, v25
	v_cvt_pk_bf16_f32 v72, v18, v19
	v_cvt_pk_bf16_f32 v73, v20, v21
	global_store_dwordx4 v[80:81], v[70:73], off offset:2048
	s_nop 1
	v_cvt_pk_bf16_f32 v70, v30, v31
	v_cvt_pk_bf16_f32 v71, v32, v33
	v_cvt_pk_bf16_f32 v72, v26, v27
	v_cvt_pk_bf16_f32 v73, v28, v29
	global_store_dwordx4 v[80:81], v[70:73], off offset:3072
	s_cbranch_vccnz .LBB0_586
	s_add_i32 s100, s10, s4
	s_cmp_lt_i32 s100, 0x8000
	s_cbranch_scc0 .Lx_a_w5
	s_waitcnt vmcnt(13)
	s_branch .Lx_a_cp
.Lx_a_w5:
	s_waitcnt vmcnt(5)
.Lx_a_cp:
	v_mov_b64_e32 v[2:3], v[34:35]
	v_mov_b64_e32 v[4:5], v[36:37]
	v_mov_b64_e32 v[6:7], v[38:39]
	v_mov_b64_e32 v[8:9], v[40:41]
	v_mov_b64_e32 v[10:11], v[42:43]
	v_mov_b64_e32 v[12:13], v[44:45]
	v_mov_b64_e32 v[14:15], v[46:47]
	v_mov_b64_e32 v[16:17], v[48:49]
	v_mov_b64_e32 v[18:19], v[50:51]
	v_mov_b64_e32 v[20:21], v[52:53]
	v_mov_b64_e32 v[22:23], v[54:55]
	v_mov_b64_e32 v[24:25], v[56:57]
	v_mov_b64_e32 v[26:27], v[58:59]
	v_mov_b64_e32 v[28:29], v[60:61]
	v_mov_b64_e32 v[30:31], v[62:63]
	v_mov_b64_e32 v[32:33], v[64:65]
	s_mov_b32 s0, s10
	s_add_i32 s10, s0, s4
	s_cmp_lt_i32 s10, 0x8000
	s_cselect_b64 s[14:15], -1, 0
	s_add_i32 s100, s10, s4
	s_cmp_lt_i32 s100, 0x8000
	s_cbranch_scc0 .Lx_b_noload
	s_ashr_i32 s101, s100, 31
	s_lshl_b64 s[20:21], s[100:101], 12
	v_lshl_add_u64 v[92:93], v[66:67], 0, s[20:21]
	s_mov_b64 s[20:21], 0x1000
	v_lshl_add_u64 v[94:95], v[92:93], 0, s[20:21]
	global_load_dwordx4 v[34:37], v[92:93], off offset:16
	global_load_dwordx4 v[38:41], v[92:93], off
	global_load_dwordx4 v[42:45], v[92:93], off offset:2064
	global_load_dwordx4 v[46:49], v[92:93], off offset:2048
	global_load_dwordx4 v[50:53], v[94:95], off offset:16
	global_load_dwordx4 v[54:57], v[94:95], off
	global_load_dwordx4 v[58:61], v[94:95], off offset:2064
	global_load_dwordx4 v[62:65], v[94:95], off offset:2048

; __device__ __forceinline__ void p0_prologue(KArgs A, LAS unsigned char* lds, int G) {
;     ...
;                 if (!hn) break;
;                 m = mn;
; #pragma unroll
;                 for (int i = 0; i < 8; ++i) v[i] = w[i];
.Lx_b_cp:
	v_mov_b64_e32 v[2:3], v[100:101]
	v_mov_b64_e32 v[4:5], v[102:103]
	v_mov_b64_e32 v[6:7], v[104:105]
	v_mov_b64_e32 v[8:9], v[106:107]
	v_mov_b64_e32 v[10:11], v[108:109]
	v_mov_b64_e32 v[12:13], v[110:111]
	v_mov_b64_e32 v[14:15], v[112:113]
	v_mov_b64_e32 v[16:17], v[114:115]
	v_mov_b64_e32 v[18:19], v[116:117]
	v_mov_b64_e32 v[20:21], v[118:119]
	v_mov_b64_e32 v[22:23], v[120:121]
	v_mov_b64_e32 v[24:25], v[122:123]
	v_mov_b64_e32 v[26:27], v[124:125]
	v_mov_b64_e32 v[28:29], v[126:127]
	v_mov_b64_e32 v[30:31], v[128:129]
	v_mov_b64_e32 v[32:33], v[130:131]
	s_mov_b32 s0, s10
	s_branch .LBB0_580
